# v49 + P0: all 32 x_prompt float4 loads per lane issued up front, ahead of the weight-transpose jobs, converted/stored after them
# baseline (speedup 1.0000x reference)
; __device__ __forceinline__ unsigned pk2(float lo, float hi) { f32x2_t v = {lo, hi}; bf16x2_t b = __builtin_convertvector(v, bf16x2_t); return __builtin_bit_cast(unsigned, b); }
; __device__ __forceinline__ void phase0(const Params& p, float* ldsf, int bid, int G) {
;     unsigned char* ws = p.ws;
;     const int nj = (G == 256) ? NJ_EARLY : NJ_ALL;
;     for (int job = bid; job < nj; job += G) weight_job<true>(p, job, ldsf);
;     bfu* xb = (bfu*)(ws + WS_XB);
;     const int NT = G * 512, gt = bid * 512 + threadIdx.x;
;     {
;         const float4* src = (const float4*)p.x_prompt; constexpr int N4 = MP * 256;
; #pragma unroll 1
;         for (int i0 = gt; i0 < N4; i0 += 8 * NT) {
;             float4 v[8];
; #pragma unroll
;             for (int k = 0; k < 8; ++k) { const int i = i0 + k * NT; v[k] = src[i < N4 ? i : N4 - 1]; }
; #pragma unroll
;             for (int k = 0; k < 8; ++k) { const int i = i0 + k * NT; if (i < N4) { uint2 o; o.x = pk2(v[k].x, v[k].y); o.y = pk2(v[k].z, v[k].w); *(uint2*)(xb + (size_t)i * 4) = o; } }
;         }
;     }
.LBB0_3:
	s_or_b64 exec, exec, s[4:5]
	v_readlane_b32 s8, v252, 1
	v_readlane_b32 s9, v252, 2
	s_cmpk_lg_i32 s92, 0x100
	s_load_dwordx2 s[6:7], s[8:9], 0xb8
	s_cselect_b64 s[0:1], -1, 0
	s_cmpk_eq_i32 s92, 0x100
	s_cselect_b64 s[12:13], -1, 0
	s_movk_i32 s3, 0x310
	s_and_b64 s[4:5], s[12:13], exec
	s_cselect_b32 s3, s3, 0x830
	v_writelane_b32 v252, s0, 3
	s_cmpk_lg_i32 s92, 0x100
	s_cbranch_scc1 .Lp0_noburst
	s_load_dwordx2 s[44:45], s[8:9], 0x0
	v_lshl_add_u32 v208, s2, 9, v172
	v_lshlrev_b32_e32 v208, 4, v208
	s_waitcnt lgkmcnt(0)
	global_load_dwordx4 v[72:75], v208, s[44:45]
	s_add_u32 s44, s44, 0x200000
	s_addc_u32 s45, s45, 0
	global_load_dwordx4 v[76:79], v208, s[44:45]
	s_add_u32 s44, s44, 0x200000
	s_addc_u32 s45, s45, 0
	global_load_dwordx4 v[80:83], v208, s[44:45]
	s_add_u32 s44, s44, 0x200000
	s_addc_u32 s45, s45, 0
	global_load_dwordx4 v[84:87], v208, s[44:45]
	s_add_u32 s44, s44, 0x200000
	s_addc_u32 s45, s45, 0
	global_load_dwordx4 v[88:91], v208, s[44:45]
	s_add_u32 s44, s44, 0x200000
	s_addc_u32 s45, s45, 0
	global_load_dwordx4 v[92:95], v208, s[44:45]
	s_add_u32 s44, s44, 0x200000
	s_addc_u32 s45, s45, 0
	global_load_dwordx4 v[96:99], v208, s[44:45]
	s_add_u32 s44, s44, 0x200000
	s_addc_u32 s45, s45, 0
	global_load_dwordx4 v[100:103], v208, s[44:45]
	s_add_u32 s44, s44, 0x200000
	s_addc_u32 s45, s45, 0
	global_load_dwordx4 v[104:107], v208, s[44:45]
	s_add_u32 s44, s44, 0x200000
	s_addc_u32 s45, s45, 0
	global_load_dwordx4 v[108:111], v208, s[44:45]
	s_add_u32 s44, s44, 0x200000
	s_addc_u32 s45, s45, 0
	global_load_dwordx4 v[112:115], v208, s[44:45]
	s_add_u32 s44, s44, 0x200000
	s_addc_u32 s45, s45, 0
	global_load_dwordx4 v[116:119], v208, s[44:45]
	s_add_u32 s44, s44, 0x200000
	s_addc_u32 s45, s45, 0
	global_load_dwordx4 v[120:123], v208, s[44:45]
	s_add_u32 s44, s44, 0x200000
	s_addc_u32 s45, s45, 0
	global_load_dwordx4 v[124:127], v208, s[44:45]
	s_add_u32 s44, s44, 0x200000
	s_addc_u32 s45, s45, 0
	global_load_dwordx4 v[128:131], v208, s[44:45]
	s_add_u32 s44, s44, 0x200000
	s_addc_u32 s45, s45, 0
	global_load_dwordx4 v[132:135], v208, s[44:45]
	s_add_u32 s44, s44, 0x200000
	s_addc_u32 s45, s45, 0
	global_load_dwordx4 v[136:139], v208, s[44:45]
	s_add_u32 s44, s44, 0x200000
	s_addc_u32 s45, s45, 0
	global_load_dwordx4 v[140:143], v208, s[44:45]
	s_add_u32 s44, s44, 0x200000
	s_addc_u32 s45, s45, 0
	global_load_dwordx4 v[144:147], v208, s[44:45]
	s_add_u32 s44, s44, 0x200000
	s_addc_u32 s45, s45, 0
	global_load_dwordx4 v[148:151], v208, s[44:45]
	s_add_u32 s44, s44, 0x200000
	s_addc_u32 s45, s45, 0
	global_load_dwordx4 v[152:155], v208, s[44:45]
	s_add_u32 s44, s44, 0x200000
	s_addc_u32 s45, s45, 0
	global_load_dwordx4 v[156:159], v208, s[44:45]
	s_add_u32 s44, s44, 0x200000
	s_addc_u32 s45, s45, 0
	global_load_dwordx4 v[160:163], v208, s[44:45]
	s_add_u32 s44, s44, 0x200000
	s_addc_u32 s45, s45, 0
	global_load_dwordx4 v[164:167], v208, s[44:45]
	s_add_u32 s44, s44, 0x200000
	s_addc_u32 s45, s45, 0
	global_load_dwordx4 v[168:171], v208, s[44:45]
	s_add_u32 s44, s44, 0x200000
	s_addc_u32 s45, s45, 0
	global_load_dwordx4 v[180:183], v208, s[44:45]
	s_add_u32 s44, s44, 0x200000
	s_addc_u32 s45, s45, 0
	global_load_dwordx4 v[184:187], v208, s[44:45]
	s_add_u32 s44, s44, 0x200000
	s_addc_u32 s45, s45, 0
	global_load_dwordx4 v[188:191], v208, s[44:45]
	s_add_u32 s44, s44, 0x200000
	s_addc_u32 s45, s45, 0
	global_load_dwordx4 v[192:195], v208, s[44:45]
	s_add_u32 s44, s44, 0x200000
	s_addc_u32 s45, s45, 0
	global_load_dwordx4 v[196:199], v208, s[44:45]
	s_add_u32 s44, s44, 0x200000
	s_addc_u32 s45, s45, 0
	global_load_dwordx4 v[200:203], v208, s[44:45]
	s_add_u32 s44, s44, 0x200000
	s_addc_u32 s45, s45, 0
	global_load_dwordx4 v[204:207], v208, s[44:45]
.Lp0_noburst:
	s_cmp_ge_i32 s2, s3
	s_nop 0
	v_writelane_b32 v252, s1, 4
	s_cbranch_scc1 .LBB0_38
	v_and_b32_e32 v3, 31, v172
	v_lshrrev_b32_e32 v1, 5, v172
	v_lshl_add_u32 v17, v3, 4, 0
	v_mul_u32_u24_e32 v4, 0x3f8, v3
	v_lshlrev_b32_e32 v5, 2, v1
	v_add3_u32 v23, v17, v4, v5
	v_mov_b32_e32 v5, 0
	v_lshlrev_b32_e32 v2, 2, v3
	v_cmp_gt_u32_e32 vcc, 4, v3
	v_mov_b32_e32 v3, v5
	s_waitcnt lgkmcnt(0)
	v_lshl_add_u64 v[6:7], s[6:7], 0, v[2:3]
	s_mov_b64 s[14:15], 0x1c00000
	v_lshl_add_u64 v[8:9], v[6:7], 0, s[14:15]
	s_mov_b64 s[14:15], 0x1100000
	v_mul_u32_u24_e32 v18, 0x204, v1
	v_lshl_add_u64 v[10:11], v[6:7], 0, s[14:15]
	s_mov_b64 s[14:15], 0xd00000
	v_lshlrev_b32_e32 v4, 11, v1
	s_lshl_b32 s10, s2, 3
	v_add_u32_e32 v27, 0x70, v1
	v_cndmask_b32_e32 v16, 0, v2, vcc
	s_movk_i32 s4, 0x200
	v_lshl_add_u64 v[12:13], v[6:7], 0, s[14:15]
	v_lshl_add_u64 v[14:15], v[6:7], 0, v[4:5]
	s_mov_b64 s[14:15], 0xc00000
	s_add_i32 s22, s10, 0x7fffc980
	s_lshl_b32 s10, s2, 6
	v_add_u32_e32 v3, v17, v18
	s_mov_b32 s11, 0
	v_add_u32_e32 v20, 16, v1
	v_or_b32_e32 v21, 32, v1
	v_add_u32_e32 v22, 48, v1
	v_or_b32_e32 v24, 64, v1
	v_add_u32_e32 v25, 0x50, v1
	v_or_b32_e32 v26, 0x60, v1
	v_add_u32_e32 v28, 0x90, v1
	v_add_u32_e32 v29, 0xb0, v1
	v_add_u32_e32 v30, 0xd0, v1
	v_and_b32_e32 v31, 0x7f, v27
	v_cmp_gt_u32_e64 s[4:5], s4, v172
	v_lshl_add_u64 v[14:15], v[14:15], 0, s[14:15]
	s_lshl_b32 s20, s2, 7
	s_lshl_b32 s21, s92, 7
	s_lshl_b32 s23, s92, 3
	s_add_i32 s14, s10, 0xffff4000
	s_lshl_b32 s24, s92, 6
	v_add_u32_e32 v32, 0x2040, v3
	v_add_u32_e32 v33, 0x2048, v3
	v_add_u32_e32 v34, 0x4080, v3
	v_add_u32_e32 v35, 0x4088, v3
	v_add_u32_e32 v36, 0x60c0, v3
	v_add_u32_e32 v37, 0x60c8, v3
	s_movk_i32 s25, 0xb00
	s_movk_i32 s26, 0x400
	s_mov_b32 s27, 0x2c000
	s_mov_b32 s28, 0x58000
	s_mov_b32 s29, 0x84000
	s_mov_b32 s30, 0x40000
	s_mov_b32 s31, 0x50000
	s_mov_b32 s33, 0x60000
	s_movk_i32 s34, 0x1f00
	v_lshlrev_b32_e32 v4, 2, v16
	s_mov_b64 s[16:17], 0x6000
	s_movk_i32 s35, 0x6040
	s_movk_i32 s36, 0x1800
	v_mov_b32_e32 v38, 0x40000
	s_mov_b32 s37, s2
	s_branch .LBB0_7

; __device__ __forceinline__ unsigned pk2(float lo, float hi) { f32x2_t v = {lo, hi}; bf16x2_t b = __builtin_convertvector(v, bf16x2_t); return __builtin_bit_cast(unsigned, b); }
; __device__ __forceinline__ void phase0(const Params& p, float* ldsf, int bid, int G) {
;     ...
;     {
;         const float4* src = (const float4*)p.x_prompt; constexpr int N4 = MP * 256;
; #pragma unroll 1
;         for (int i0 = gt; i0 < N4; i0 += 8 * NT) {
;             float4 v[8];
; #pragma unroll
;             for (int k = 0; k < 8; ++k) { const int i = i0 + k * NT; v[k] = src[i < N4 ? i : N4 - 1]; }
; #pragma unroll
;             for (int k = 0; k < 8; ++k) { const int i = i0 + k * NT; if (i < N4) { uint2 o; o.x = pk2(v[k].x, v[k].y); o.y = pk2(v[k].z, v[k].w); *(uint2*)(xb + (size_t)i * 4) = o; } }
;         }
;     }
.LBB0_38:
	v_lshl_add_u32 v178, s2, 9, v172
	s_mov_b32 s3, 0x400000
	s_lshl_b32 s40, s92, 9
	s_cmpk_lg_i32 s92, 0x100
	s_cbranch_scc1 .Lp0_orig_xloop
	s_add_u32 s46, s6, 0x2200000
	s_addc_u32 s47, s7, 0
	v_lshrrev_b32_e32 v208, 1, v208
	v_mov_b32_e32 v209, 0
	v_lshl_add_u64 v[208:209], s[46:47], 0, v[208:209]
	s_mov_b64 s[46:47], 0x100000
	s_waitcnt vmcnt(31)
	v_cvt_pk_bf16_f32 v72, v72, v73
	v_cvt_pk_bf16_f32 v73, v74, v75
	global_store_dwordx2 v[208:209], v[72:73], off
	v_lshl_add_u64 v[208:209], v[208:209], 0, s[46:47]
	s_waitcnt vmcnt(31)
	v_cvt_pk_bf16_f32 v76, v76, v77
	v_cvt_pk_bf16_f32 v77, v78, v79
	global_store_dwordx2 v[208:209], v[76:77], off
	v_lshl_add_u64 v[208:209], v[208:209], 0, s[46:47]
	s_waitcnt vmcnt(31)
	v_cvt_pk_bf16_f32 v80, v80, v81
	v_cvt_pk_bf16_f32 v81, v82, v83
	global_store_dwordx2 v[208:209], v[80:81], off
	v_lshl_add_u64 v[208:209], v[208:209], 0, s[46:47]
	s_waitcnt vmcnt(31)
	v_cvt_pk_bf16_f32 v84, v84, v85
	v_cvt_pk_bf16_f32 v85, v86, v87
	global_store_dwordx2 v[208:209], v[84:85], off
	v_lshl_add_u64 v[208:209], v[208:209], 0, s[46:47]
	s_waitcnt vmcnt(31)
	v_cvt_pk_bf16_f32 v88, v88, v89
	v_cvt_pk_bf16_f32 v89, v90, v91
	global_store_dwordx2 v[208:209], v[88:89], off
	v_lshl_add_u64 v[208:209], v[208:209], 0, s[46:47]
	s_waitcnt vmcnt(31)
	v_cvt_pk_bf16_f32 v92, v92, v93
	v_cvt_pk_bf16_f32 v93, v94, v95
	global_store_dwordx2 v[208:209], v[92:93], off
	v_lshl_add_u64 v[208:209], v[208:209], 0, s[46:47]
	s_waitcnt vmcnt(31)
	v_cvt_pk_bf16_f32 v96, v96, v97
	v_cvt_pk_bf16_f32 v97, v98, v99
	global_store_dwordx2 v[208:209], v[96:97], off
	v_lshl_add_u64 v[208:209], v[208:209], 0, s[46:47]
	s_waitcnt vmcnt(31)
	v_cvt_pk_bf16_f32 v100, v100, v101
	v_cvt_pk_bf16_f32 v101, v102, v103
	global_store_dwordx2 v[208:209], v[100:101], off
	v_lshl_add_u64 v[208:209], v[208:209], 0, s[46:47]
	s_waitcnt vmcnt(31)
	v_cvt_pk_bf16_f32 v104, v104, v105
	v_cvt_pk_bf16_f32 v105, v106, v107
	global_store_dwordx2 v[208:209], v[104:105], off
	v_lshl_add_u64 v[208:209], v[208:209], 0, s[46:47]
	s_waitcnt vmcnt(31)
	v_cvt_pk_bf16_f32 v108, v108, v109
	v_cvt_pk_bf16_f32 v109, v110, v111
	global_store_dwordx2 v[208:209], v[108:109], off
	v_lshl_add_u64 v[208:209], v[208:209], 0, s[46:47]
	s_waitcnt vmcnt(31)
	v_cvt_pk_bf16_f32 v112, v112, v113
	v_cvt_pk_bf16_f32 v113, v114, v115
	global_store_dwordx2 v[208:209], v[112:113], off
	v_lshl_add_u64 v[208:209], v[208:209], 0, s[46:47]
	s_waitcnt vmcnt(31)
	v_cvt_pk_bf16_f32 v116, v116, v117
	v_cvt_pk_bf16_f32 v117, v118, v119
	global_store_dwordx2 v[208:209], v[116:117], off
	v_lshl_add_u64 v[208:209], v[208:209], 0, s[46:47]
	s_waitcnt vmcnt(31)
	v_cvt_pk_bf16_f32 v120, v120, v121
	v_cvt_pk_bf16_f32 v121, v122, v123
	global_store_dwordx2 v[208:209], v[120:121], off
	v_lshl_add_u64 v[208:209], v[208:209], 0, s[46:47]
	s_waitcnt vmcnt(31)
	v_cvt_pk_bf16_f32 v124, v124, v125
	v_cvt_pk_bf16_f32 v125, v126, v127
	global_store_dwordx2 v[208:209], v[124:125], off
	v_lshl_add_u64 v[208:209], v[208:209], 0, s[46:47]
	s_waitcnt vmcnt(31)
	v_cvt_pk_bf16_f32 v128, v128, v129
	v_cvt_pk_bf16_f32 v129, v130, v131
	global_store_dwordx2 v[208:209], v[128:129], off
	v_lshl_add_u64 v[208:209], v[208:209], 0, s[46:47]
	s_waitcnt vmcnt(31)
	v_cvt_pk_bf16_f32 v132, v132, v133
	v_cvt_pk_bf16_f32 v133, v134, v135
	global_store_dwordx2 v[208:209], v[132:133], off
	v_lshl_add_u64 v[208:209], v[208:209], 0, s[46:47]
	s_waitcnt vmcnt(31)
	v_cvt_pk_bf16_f32 v136, v136, v137
	v_cvt_pk_bf16_f32 v137, v138, v139
	global_store_dwordx2 v[208:209], v[136:137], off
	v_lshl_add_u64 v[208:209], v[208:209], 0, s[46:47]
	s_waitcnt vmcnt(31)
	v_cvt_pk_bf16_f32 v140, v140, v141
	v_cvt_pk_bf16_f32 v141, v142, v143
	global_store_dwordx2 v[208:209], v[140:141], off
	v_lshl_add_u64 v[208:209], v[208:209], 0, s[46:47]
	s_waitcnt vmcnt(31)
	v_cvt_pk_bf16_f32 v144, v144, v145
	v_cvt_pk_bf16_f32 v145, v146, v147
	global_store_dwordx2 v[208:209], v[144:145], off
	v_lshl_add_u64 v[208:209], v[208:209], 0, s[46:47]
	s_waitcnt vmcnt(31)
	v_cvt_pk_bf16_f32 v148, v148, v149
	v_cvt_pk_bf16_f32 v149, v150, v151
	global_store_dwordx2 v[208:209], v[148:149], off
	v_lshl_add_u64 v[208:209], v[208:209], 0, s[46:47]
	s_waitcnt vmcnt(31)
	v_cvt_pk_bf16_f32 v152, v152, v153
	v_cvt_pk_bf16_f32 v153, v154, v155
	global_store_dwordx2 v[208:209], v[152:153], off
	v_lshl_add_u64 v[208:209], v[208:209], 0, s[46:47]
	s_waitcnt vmcnt(31)
	v_cvt_pk_bf16_f32 v156, v156, v157
	v_cvt_pk_bf16_f32 v157, v158, v159
	global_store_dwordx2 v[208:209], v[156:157], off
	v_lshl_add_u64 v[208:209], v[208:209], 0, s[46:47]
	s_waitcnt vmcnt(31)
	v_cvt_pk_bf16_f32 v160, v160, v161
	v_cvt_pk_bf16_f32 v161, v162, v163
	global_store_dwordx2 v[208:209], v[160:161], off
	v_lshl_add_u64 v[208:209], v[208:209], 0, s[46:47]
	s_waitcnt vmcnt(31)
	v_cvt_pk_bf16_f32 v164, v164, v165
	v_cvt_pk_bf16_f32 v165, v166, v167
	global_store_dwordx2 v[208:209], v[164:165], off
	v_lshl_add_u64 v[208:209], v[208:209], 0, s[46:47]
	s_waitcnt vmcnt(31)
	v_cvt_pk_bf16_f32 v168, v168, v169
	v_cvt_pk_bf16_f32 v169, v170, v171
	global_store_dwordx2 v[208:209], v[168:169], off
	v_lshl_add_u64 v[208:209], v[208:209], 0, s[46:47]
	s_waitcnt vmcnt(31)
	v_cvt_pk_bf16_f32 v180, v180, v181
	v_cvt_pk_bf16_f32 v181, v182, v183
	global_store_dwordx2 v[208:209], v[180:181], off
	v_lshl_add_u64 v[208:209], v[208:209], 0, s[46:47]
	s_waitcnt vmcnt(31)
	v_cvt_pk_bf16_f32 v184, v184, v185
	v_cvt_pk_bf16_f32 v185, v186, v187
	global_store_dwordx2 v[208:209], v[184:185], off
	v_lshl_add_u64 v[208:209], v[208:209], 0, s[46:47]
	s_waitcnt vmcnt(31)
	v_cvt_pk_bf16_f32 v188, v188, v189
	v_cvt_pk_bf16_f32 v189, v190, v191
	global_store_dwordx2 v[208:209], v[188:189], off
	v_lshl_add_u64 v[208:209], v[208:209], 0, s[46:47]
	s_waitcnt vmcnt(31)
	v_cvt_pk_bf16_f32 v192, v192, v193
	v_cvt_pk_bf16_f32 v193, v194, v195
	global_store_dwordx2 v[208:209], v[192:193], off
	v_lshl_add_u64 v[208:209], v[208:209], 0, s[46:47]
	s_waitcnt vmcnt(31)
	v_cvt_pk_bf16_f32 v196, v196, v197
	v_cvt_pk_bf16_f32 v197, v198, v199
	global_store_dwordx2 v[208:209], v[196:197], off
	v_lshl_add_u64 v[208:209], v[208:209], 0, s[46:47]
	s_waitcnt vmcnt(31)
	v_cvt_pk_bf16_f32 v200, v200, v201
	v_cvt_pk_bf16_f32 v201, v202, v203
	global_store_dwordx2 v[208:209], v[200:201], off
	v_lshl_add_u64 v[208:209], v[208:209], 0, s[46:47]
	s_waitcnt vmcnt(31)
	v_cvt_pk_bf16_f32 v204, v204, v205
	v_cvt_pk_bf16_f32 v205, v206, v207
	global_store_dwordx2 v[208:209], v[204:205], off
	s_mov_b64 s[4:5], exec
	s_branch .LBB0_55
.Lp0_orig_xloop:
	v_cmp_gt_i32_e32 vcc, s3, v178
	s_and_saveexec_b64 s[4:5], vcc
	s_cbranch_execz .LBB0_55
	s_load_dwordx2 s[14:15], s[8:9], 0x0
	s_waitcnt lgkmcnt(0)
	s_add_u32 s10, s6, 0x2200000
	s_addc_u32 s11, s7, 0
	s_lshl_b32 s20, s92, 10
	s_mul_i32 s21, s92, 0x600
	s_lshl_b32 s22, s92, 11
	s_mul_i32 s23, s92, 0xa00
	s_mul_i32 s24, s92, 0xc00
	s_mul_i32 s25, s92, 0xe00
	s_mov_b64 s[16:17], 0
	s_mov_b32 s26, 0x3fffff
	v_mov_b32_e32 v44, v178
	s_branch .LBB0_41
